# weight conversion spread over 192 workgroups and split across both layers proj tails
# speedup vs baseline: 1.0030x; 1.0030x over previous
.LBB0_1204:
	v_readlane_b32 s0, v255, 2
	v_readlane_b32 s1, v255, 3
	s_mov_b64 vcc, 0
	s_waitcnt vmcnt(0)
	s_barrier
	s_cbranch_vccnz .LBB0_1272
	s_and_b64 vcc, exec, s[66:67]
	s_cbranch_vccnz .LBB0_1207
	s_cmp_gt_i32 s29, 0x7f
	s_cselect_b64 s[0:1], -1, 0
	s_or_b64 s[64:65], s[64:65], s[0:1]
	s_cbranch_execz .LBB0_1208
	s_branch .LBB0_1209

.LBB0_1209:
	s_andn2_b64 vcc, exec, s[64:65]
	s_cbranch_vccnz .LBB0_1272
	v_readlane_b32 s0, v252, 11
	v_mbcnt_lo_u32_b32 v0, -1, 0
	v_mbcnt_hi_u32_b32 v0, -1, v0
	s_and_b64 vcc, exec, s[66:67]
	s_nop 0
	v_add_u32_e32 v1, s0, v0
	s_mov_b64 s[0:1], -1
	v_and_b32_e32 v5, 63, v1
	s_cbranch_vccnz .LBB0_1241
	s_lshl_b32 s0, s29, 2
	s_and_b32 s0, s0, -8
	s_bitcmp1_b32 s29, 0
	s_cselect_b32 s1, 0, 0x200
	s_add_i32 s0, s0, s1
	v_readlane_b32 s1, v252, 6
	s_add_i32 s0, s0, s1
	s_cmpk_gt_i32 s0, 0x387f
	s_cbranch_scc1 .LBB0_1240
	v_lshrrev_b32_e32 v10, 5, v5
	v_and_b32_e32 v0, 31, v1
	v_readlane_b32 s100, v255, 12
	s_nop 1
	s_mul_i32 s101, s100, 0x2800
	s_addk_i32 s101, 0xe80
	s_mul_i32 s100, s100, 0x1080
	s_addk_i32 s100, 0x307f
	s_add_i32 s14, s0, s101
	v_lshlrev_b32_e32 v2, 2, v0
	v_mul_u32_u24_e32 v4, 0x84, v10
	v_readlane_b32 s0, v252, 7
	v_lshrrev_b32_e32 v12, 3, v5
	v_lshlrev_b32_e32 v6, 2, v12
	v_add3_u32 v11, s0, v2, v4
	v_lshlrev_b32_e32 v2, 3, v5
	v_and_b32_e32 v4, 56, v2
	v_mul_u32_u24_e32 v2, 0x84, v4
	s_cmp_lg_u64 s[54:55], 0
	v_add3_u32 v13, s0, v2, v6
	s_cselect_b64 s[0:1], -1, 0
	v_lshlrev_b32_e32 v2, 1, v5
	s_cmp_lg_u64 s[44:45], 0
	v_or_b32_e32 v14, 8, v12
	v_or_b32_e32 v15, 16, v12
	v_or_b32_e32 v16, 24, v12
	v_and_b32_e32 v17, 62, v2
	v_and_b32_e32 v18, 32, v1
	s_cselect_b64 s[4:5], -1, 0
	s_lshl_b32 s15, s14, 1
	s_lshl_b32 s16, s14, 5
	s_branch .LBB0_1216

.LBB0_1215:
	s_add_i32 s2, s14, 0x600
	s_addk_i32 s15, 0xc00
	s_add_i32 s16, s16, 0xc000
	s_cmp_gt_i32 s14, s100
	s_mov_b32 s14, s2
	s_cbranch_scc1 .LBB0_1240

	.amdhsa_kernel _Z3fwd4Args
		.amdhsa_group_segment_fixed_size 0
		.amdhsa_private_segment_fixed_size 0
		.amdhsa_kernarg_size 400
		.amdhsa_user_sgpr_count 2
		.amdhsa_user_sgpr_dispatch_ptr 0
		.amdhsa_user_sgpr_queue_ptr 0
		.amdhsa_user_sgpr_kernarg_segment_ptr 1
		.amdhsa_user_sgpr_dispatch_id 0
		.amdhsa_user_sgpr_kernarg_preload_length 0
		.amdhsa_user_sgpr_kernarg_preload_offset 0
		.amdhsa_user_sgpr_private_segment_size 0
		.amdhsa_uses_dynamic_stack 0
		.amdhsa_enable_private_segment 0
		.amdhsa_system_sgpr_workgroup_id_x 1
		.amdhsa_system_sgpr_workgroup_id_y 0
		.amdhsa_system_sgpr_workgroup_id_z 0
		.amdhsa_system_sgpr_workgroup_info 0
		.amdhsa_system_vgpr_workitem_id 0
		.amdhsa_next_free_vgpr 256
		.amdhsa_next_free_sgpr 102
		.amdhsa_accum_offset 256
		.amdhsa_reserve_vcc 1
		.amdhsa_float_round_mode_32 0
		.amdhsa_float_round_mode_16_64 0
		.amdhsa_float_denorm_mode_32 3
		.amdhsa_float_denorm_mode_16_64 3
		.amdhsa_dx10_clamp 1
		.amdhsa_ieee_mode 1
		.amdhsa_fp16_overflow 0
		.amdhsa_tg_split 0
		.amdhsa_exception_fp_ieee_invalid_op 0
		.amdhsa_exception_fp_denorm_src 0
		.amdhsa_exception_fp_ieee_div_zero 0
		.amdhsa_exception_fp_ieee_overflow 0
		.amdhsa_exception_fp_ieee_underflow 0
		.amdhsa_exception_fp_ieee_inexact 0
		.amdhsa_exception_int_div_zero 0
	.end_amdhsa_kernel

amdhsa.kernels:
  - .agpr_count:     0
    .args:
      - .offset:         0
        .size:           144
        .value_kind:     by_value
      - .offset:         144
        .size:           4
        .value_kind:     hidden_block_count_x
      - .offset:         148
        .size:           4
        .value_kind:     hidden_block_count_y
      - .offset:         152
        .size:           4
        .value_kind:     hidden_block_count_z
      - .offset:         156
        .size:           2
        .value_kind:     hidden_group_size_x
      - .offset:         158
        .size:           2
        .value_kind:     hidden_group_size_y
      - .offset:         160
        .size:           2
        .value_kind:     hidden_group_size_z
      - .offset:         162
        .size:           2
        .value_kind:     hidden_remainder_x
      - .offset:         164
        .size:           2
        .value_kind:     hidden_remainder_y
      - .offset:         166
        .size:           2
        .value_kind:     hidden_remainder_z
      - .offset:         184
        .size:           8
        .value_kind:     hidden_global_offset_x
      - .offset:         192
        .size:           8
        .value_kind:     hidden_global_offset_y
      - .offset:         200
        .size:           8
        .value_kind:     hidden_global_offset_z
      - .offset:         208
        .size:           2
        .value_kind:     hidden_grid_dims
      - .offset:         264
        .size:           4
        .value_kind:     hidden_dynamic_lds_size
    .group_segment_fixed_size: 0
    .kernarg_segment_align: 8
    .kernarg_segment_size: 400
    .language:       OpenCL C
    .language_version:
      - 2
      - 0
    .max_flat_workgroup_size: 512
    .name:           _Z3fwd4Args
    .private_segment_fixed_size: 0
    .sgpr_count:     108
    .sgpr_spill_count: 263
    .symbol:         _Z3fwd4Args.kd
    .uniform_work_group_size: 1
    .uses_dynamic_stack: false
    .vgpr_count:     256
    .vgpr_spill_count: 0
    .wavefront_size: 64
